# FFN1-out fused epilogue: residual (x) loads kept three groups ahead in spare registers instead of one group per memory round trip; plus earlier conv-phase hoist and write-through stores
# speedup vs baseline: 1.0029x; 1.0019x over previous
.LBB0_243:
	s_lshl_b32 s28, s17, 5
	v_and_b32_e32 v191, 12, v108
	s_ashr_i32 s0, s6, 4
	s_lshl_b32 s64, s6, 8
	s_lshl_b32 s18, s20, 8
	v_or_b32_e32 v192, s28, v191
	s_mul_hi_i32 s1, s0, 0x2400
	s_mulk_i32 s0, 0x2400
	s_add_i32 s2, s64, s63
	v_or_b32_e32 v94, s18, v192
	s_lshl_b64 s[14:15], s[0:1], 2
	s_add_u32 s0, s58, s14
	v_ashrrev_i32_e32 v95, 31, v94
	s_addc_u32 s1, s59, s15
	v_lshlrev_b64 v[142:143], 2, v[94:95]
	v_lshl_add_u64 v[94:95], s[0:1], 0, v[142:143]
	s_mov_b64 s[0:1], 0x102000
	v_lshl_add_u64 v[144:145], v[94:95], 0, s[0:1]
	s_mov_b32 s0, 0x102000
	v_add_co_u32_e32 v94, vcc, s0, v94
	v_or_b32_e32 v182, s2, v190
	v_readlane_b32 s80, v254, 2
	v_addc_co_u32_e32 v95, vcc, 0, v95, vcc
	v_ashrrev_i32_e32 v183, 31, v182
	v_readlane_b32 s81, v254, 3
	s_barrier
	global_load_dwordx4 v[94:97], v[94:95], off
	s_nop 0
	global_load_dwordx4 v[106:109], v[144:145], off offset:64
	global_load_dwordx4 v[110:113], v[144:145], off offset:512
	global_load_dwordx4 v[162:165], v[144:145], off offset:576
	v_lshlrev_b64 v[144:145], 12, v[182:183]
	s_mov_b64 s[76:77], s[80:81]
	v_lshl_add_u64 v[144:145], s[76:77], 0, v[144:145]
	v_lshl_add_u64 v[160:161], v[144:145], 0, v[142:143]
	global_load_dwordx4 v[166:169], v[160:161], off nt
	global_load_dwordx4 v[170:173], v[160:161], off offset:64 nt
	global_load_dwordx4 v[174:177], v[160:161], off offset:512 nt
	global_load_dwordx4 v[178:181], v[160:161], off offset:576 nt
	s_mov_b32 s98, 0x10000
	s_mov_b32 s99, 0
	v_lshl_add_u64 v[244:245], v[160:161], 0, s[98:99]
	global_load_dwordx4 v[196:199], v[244:245], off nt
	global_load_dwordx4 v[200:203], v[244:245], off offset:64 nt
	global_load_dwordx4 v[204:207], v[244:245], off offset:512 nt
	global_load_dwordx4 v[208:211], v[244:245], off offset:576 nt
	s_mov_b32 s98, 0x20000
	s_mov_b32 s99, 0
	v_lshl_add_u64 v[244:245], v[160:161], 0, s[98:99]
	global_load_dwordx4 v[212:215], v[244:245], off nt
	global_load_dwordx4 v[216:219], v[244:245], off offset:64 nt
	global_load_dwordx4 v[220:223], v[244:245], off offset:512 nt
	global_load_dwordx4 v[224:227], v[244:245], off offset:576 nt
	s_mov_b32 s98, 0x30000
	s_mov_b32 s99, 0
	v_lshl_add_u64 v[244:245], v[160:161], 0, s[98:99]
	global_load_dwordx4 v[228:231], v[244:245], off nt
	global_load_dwordx4 v[232:235], v[244:245], off offset:64 nt
	global_load_dwordx4 v[236:239], v[244:245], off offset:512 nt
	global_load_dwordx4 v[240:243], v[244:245], off offset:576 nt
	v_or_b32_e32 v144, 16, v182
	v_ashrrev_i32_e32 v145, 31, v144
	v_lshlrev_b64 v[144:145], 12, v[144:145]
	v_lshl_add_u64 v[144:145], s[76:77], 0, v[144:145]
	v_lshl_add_u64 v[184:185], v[144:145], 0, v[142:143]
	s_mov_b32 s2, 0x80000
	s_mov_b64 s[0:1], 0x80000
	v_readlane_b32 s82, v254, 4
	v_readlane_b32 s83, v254, 5
	v_readlane_b32 s84, v254, 6
	v_readlane_b32 s85, v254, 7
	v_readlane_b32 s86, v254, 8
	v_readlane_b32 s87, v254, 9
	v_readlane_b32 s88, v254, 10
	v_readlane_b32 s89, v254, 11
	v_readlane_b32 s90, v254, 12
	v_readlane_b32 s91, v254, 13
	v_readlane_b32 s92, v254, 14
	v_readlane_b32 s93, v254, 15
	v_readlane_b32 s94, v254, 16
	v_readlane_b32 s95, v254, 17
	s_waitcnt vmcnt(12)
	v_pk_mul_f32 v[144:145], v[96:97], 0.5 op_sel_hi:[1,0]
	v_pk_mul_f32 v[146:147], v[94:95], 0.5 op_sel_hi:[1,0]
	v_pk_mul_f32 v[148:149], v[108:109], 0.5 op_sel_hi:[1,0]
	v_pk_mul_f32 v[150:151], v[106:107], 0.5 op_sel_hi:[1,0]
	v_pk_mul_f32 v[152:153], v[112:113], 0.5 op_sel_hi:[1,0]
	v_pk_mul_f32 v[154:155], v[110:111], 0.5 op_sel_hi:[1,0]
	v_pk_mul_f32 v[156:157], v[164:165], 0.5 op_sel_hi:[1,0]
	v_pk_mul_f32 v[158:159], v[162:163], 0.5 op_sel_hi:[1,0]
	v_pk_fma_f32 v[112:113], v[80:81], v[144:145], v[168:169]
	v_pk_fma_f32 v[110:111], v[78:79], v[146:147], v[166:167]
	v_pk_fma_f32 v[96:97], v[40:41], v[148:149], v[172:173]
	v_pk_fma_f32 v[94:95], v[38:39], v[150:151], v[170:171]
	v_pk_fma_f32 v[80:81], v[100:101], v[152:153], v[176:177]
	v_pk_fma_f32 v[78:79], v[98:99], v[154:155], v[174:175]
	v_pk_fma_f32 v[40:41], v[84:85], v[156:157], v[180:181]
	v_pk_fma_f32 v[38:39], v[82:83], v[158:159], v[178:179]
	v_or_b32_e32 v98, 32, v182
	s_waitcnt vmcnt(8)
	v_mov_b32_e32 v82, v196
	v_mov_b32_e32 v83, v197
	v_mov_b32_e32 v84, v198
	v_mov_b32_e32 v85, v199
	v_mov_b32_e32 v106, v200
	v_mov_b32_e32 v107, v201
	v_mov_b32_e32 v108, v202
	v_mov_b32_e32 v109, v203
	v_mov_b32_e32 v162, v204
	v_mov_b32_e32 v163, v205
	v_mov_b32_e32 v164, v206
	v_mov_b32_e32 v165, v207
	v_mov_b32_e32 v166, v208
	v_mov_b32_e32 v167, v209
	v_mov_b32_e32 v168, v210
	v_mov_b32_e32 v169, v211
	s_mov_b32 s98, 0x80000
	s_mov_b32 s99, 0
	v_lshl_add_u64 v[244:245], v[160:161], 0, s[98:99]
	global_load_dwordx4 v[196:199], v[244:245], off nt
	global_load_dwordx4 v[200:203], v[244:245], off offset:64 nt
	global_load_dwordx4 v[204:207], v[244:245], off offset:512 nt
	global_load_dwordx4 v[208:211], v[244:245], off offset:576 nt
	v_ashrrev_i32_e32 v99, 31, v98
	v_lshlrev_b64 v[98:99], 12, v[98:99]
	v_lshl_add_u64 v[98:99], s[76:77], 0, v[98:99]
	v_lshl_add_u64 v[170:171], v[98:99], 0, v[142:143]
	v_mul_f32_e32 v172, v79, v79
	v_mul_f32_e32 v173, v81, v81
	v_mul_f32_e32 v174, v39, v39
	v_mul_f32_e32 v175, v41, v41
	v_fmac_f32_e32 v172, v78, v78
	v_fmac_f32_e32 v173, v80, v80
	v_fmac_f32_e32 v174, v38, v38
	v_fmac_f32_e32 v175, v40, v40
	s_nop 0
	v_pk_fma_f32 v[100:101], v[64:65], v[144:145], v[84:85]
	v_pk_fma_f32 v[98:99], v[62:63], v[146:147], v[82:83]
	s_nop 0
	v_pk_fma_f32 v[84:85], v[36:37], v[148:149], v[108:109]
	v_pk_fma_f32 v[82:83], v[34:35], v[150:151], v[106:107]
	s_nop 0
	v_pk_fma_f32 v[64:65], v[104:105], v[152:153], v[164:165]
	v_pk_fma_f32 v[62:63], v[102:103], v[154:155], v[162:163]
	s_nop 0
	v_pk_fma_f32 v[36:37], v[88:89], v[156:157], v[168:169]
	v_pk_fma_f32 v[34:35], v[86:87], v[158:159], v[166:167]
	v_or_b32_e32 v102, 48, v182
	s_waitcnt vmcnt(8)
	v_mov_b32_e32 v86, v212
	v_mov_b32_e32 v87, v213
	v_mov_b32_e32 v88, v214
	v_mov_b32_e32 v89, v215
	v_mov_b32_e32 v106, v216
	v_mov_b32_e32 v107, v217
	v_mov_b32_e32 v108, v218
	v_mov_b32_e32 v109, v219
	v_mov_b32_e32 v162, v220
	v_mov_b32_e32 v163, v221
	v_mov_b32_e32 v164, v222
	v_mov_b32_e32 v165, v223
	v_mov_b32_e32 v166, v224
	v_mov_b32_e32 v167, v225
	v_mov_b32_e32 v168, v226
	v_mov_b32_e32 v169, v227
	s_mov_b32 s98, 0x90000
	s_mov_b32 s99, 0
	v_lshl_add_u64 v[244:245], v[160:161], 0, s[98:99]
	global_load_dwordx4 v[212:215], v[244:245], off nt
	global_load_dwordx4 v[216:219], v[244:245], off offset:64 nt
	global_load_dwordx4 v[220:223], v[244:245], off offset:512 nt
	global_load_dwordx4 v[224:227], v[244:245], off offset:576 nt
	v_ashrrev_i32_e32 v103, 31, v102
	v_lshlrev_b64 v[102:103], 12, v[102:103]
	v_lshl_add_u64 v[102:103], s[76:77], 0, v[102:103]
	v_lshl_add_u64 v[170:171], v[102:103], 0, v[142:143]
	s_nop 0
	v_pk_fma_f32 v[104:105], v[72:73], v[144:145], v[88:89]
	v_pk_fma_f32 v[102:103], v[70:71], v[146:147], v[86:87]
	s_nop 0
	v_pk_fma_f32 v[88:89], v[48:49], v[148:149], v[108:109]
	v_pk_fma_f32 v[86:87], v[46:47], v[150:151], v[106:107]
	s_nop 0
	v_pk_fma_f32 v[72:73], v[92:93], v[152:153], v[164:165]
	v_pk_fma_f32 v[70:71], v[90:91], v[154:155], v[162:163]
	s_nop 0
	v_pk_fma_f32 v[48:49], v[76:77], v[156:157], v[168:169]
	v_pk_fma_f32 v[46:47], v[74:75], v[158:159], v[166:167]
	s_nop 0
	s_waitcnt vmcnt(8)
	v_mov_b32_e32 v74, v228
	v_mov_b32_e32 v75, v229
	v_mov_b32_e32 v76, v230
	v_mov_b32_e32 v77, v231
	v_mov_b32_e32 v90, v232
	v_mov_b32_e32 v91, v233
	v_mov_b32_e32 v92, v234
	v_mov_b32_e32 v93, v235
	v_mov_b32_e32 v162, v236
	v_mov_b32_e32 v163, v237
	v_mov_b32_e32 v164, v238
	v_mov_b32_e32 v165, v239
	v_mov_b32_e32 v166, v240
	v_mov_b32_e32 v167, v241
	v_mov_b32_e32 v168, v242
	v_mov_b32_e32 v169, v243
	s_mov_b32 s98, 0xa0000
	s_mov_b32 s99, 0
	v_lshl_add_u64 v[244:245], v[160:161], 0, s[98:99]
	global_load_dwordx4 v[228:231], v[244:245], off nt
	global_load_dwordx4 v[232:235], v[244:245], off offset:64 nt
	global_load_dwordx4 v[236:239], v[244:245], off offset:512 nt
	global_load_dwordx4 v[240:243], v[244:245], off offset:576 nt
	v_add_co_u32_e32 v170, vcc, s2, v160
	s_mov_b32 s2, 0x90000
	s_nop 0
	v_addc_co_u32_e32 v171, vcc, 0, v161, vcc
	s_nop 0
	v_pk_fma_f32 v[108:109], v[16:17], v[144:145], v[76:77]
	v_pk_fma_f32 v[106:107], v[14:15], v[146:147], v[74:75]
	s_nop 0
	v_pk_fma_f32 v[92:93], v[4:5], v[148:149], v[92:93]
	v_pk_fma_f32 v[90:91], v[2:3], v[150:151], v[90:91]
	s_nop 0
	v_pk_fma_f32 v[76:77], v[56:57], v[152:153], v[164:165]
	v_pk_fma_f32 v[74:75], v[54:55], v[154:155], v[162:163]
	s_nop 0
	v_pk_fma_f32 v[52:53], v[52:53], v[156:157], v[168:169]
	v_pk_fma_f32 v[50:51], v[50:51], v[158:159], v[166:167]
	v_lshl_add_u64 v[54:55], v[160:161], 0, s[0:1]
	s_waitcnt vmcnt(8)
	v_mov_b32_e32 v2, v196
	v_mov_b32_e32 v3, v197
	v_mov_b32_e32 v4, v198
	v_mov_b32_e32 v5, v199
	v_mov_b32_e32 v14, v200
	v_mov_b32_e32 v15, v201
	v_mov_b32_e32 v16, v202
	v_mov_b32_e32 v17, v203
	v_mov_b32_e32 v162, v204
	v_mov_b32_e32 v163, v205
	v_mov_b32_e32 v164, v206
	v_mov_b32_e32 v165, v207
	v_mov_b32_e32 v166, v208
	v_mov_b32_e32 v167, v209
	v_mov_b32_e32 v168, v210
	v_mov_b32_e32 v169, v211
	s_mov_b32 s98, 0xb0000
	s_mov_b32 s99, 0
	v_lshl_add_u64 v[244:245], v[160:161], 0, s[98:99]
	global_load_dwordx4 v[196:199], v[244:245], off nt
	global_load_dwordx4 v[200:203], v[244:245], off offset:64 nt
	global_load_dwordx4 v[204:207], v[244:245], off offset:512 nt
	global_load_dwordx4 v[208:211], v[244:245], off offset:576 nt
	s_mov_b64 s[0:1], 0x90000
	v_add_co_u32_e32 v170, vcc, s2, v160
	s_mov_b32 s2, 0xa0000
	s_nop 0
	v_addc_co_u32_e32 v171, vcc, 0, v161, vcc
	s_nop 0
	v_pk_fma_f32 v[28:29], v[28:29], v[148:149], v[16:17]
	v_pk_fma_f32 v[56:57], v[32:33], v[144:145], v[4:5]
	v_pk_fma_f32 v[54:55], v[30:31], v[146:147], v[2:3]
	v_pk_fma_f32 v[26:27], v[26:27], v[150:151], v[14:15]
	s_nop 0
	v_pk_fma_f32 v[16:17], v[140:141], v[152:153], v[164:165]
	v_pk_fma_f32 v[14:15], v[138:139], v[154:155], v[162:163]
	s_nop 0
	v_pk_fma_f32 v[4:5], v[60:61], v[156:157], v[168:169]
	v_pk_fma_f32 v[2:3], v[58:59], v[158:159], v[166:167]
	v_lshl_add_u64 v[58:59], v[160:161], 0, s[0:1]
	s_waitcnt vmcnt(8)
	v_mov_b32_e32 v30, v212
	v_mov_b32_e32 v31, v213
	v_mov_b32_e32 v32, v214
	v_mov_b32_e32 v33, v215
	v_mov_b32_e32 v138, v216
	v_mov_b32_e32 v139, v217
	v_mov_b32_e32 v140, v218
	v_mov_b32_e32 v141, v219
	v_mov_b32_e32 v162, v220
	v_mov_b32_e32 v163, v221
	v_mov_b32_e32 v164, v222
	v_mov_b32_e32 v165, v223
	v_mov_b32_e32 v166, v224
	v_mov_b32_e32 v167, v225
	v_mov_b32_e32 v168, v226
	v_mov_b32_e32 v169, v227
	s_mov_b64 s[0:1], 0xa0000
	v_add_co_u32_e32 v170, vcc, s2, v160
	s_mov_b32 s2, 0xb0000
	s_nop 0
	v_addc_co_u32_e32 v171, vcc, 0, v161, vcc
	s_nop 0
	v_pk_fma_f32 v[60:61], v[20:21], v[144:145], v[32:33]
	v_pk_fma_f32 v[58:59], v[18:19], v[146:147], v[30:31]
	s_nop 0
	v_pk_fma_f32 v[32:33], v[8:9], v[148:149], v[140:141]
	v_pk_fma_f32 v[30:31], v[6:7], v[150:151], v[138:139]
	s_nop 0
	v_pk_fma_f32 v[20:21], v[68:69], v[152:153], v[164:165]
	v_pk_fma_f32 v[18:19], v[66:67], v[154:155], v[162:163]
	s_nop 0
	v_pk_fma_f32 v[8:9], v[44:45], v[156:157], v[168:169]
	v_pk_fma_f32 v[6:7], v[42:43], v[158:159], v[166:167]
	v_lshl_add_u64 v[66:67], v[160:161], 0, s[0:1]
	s_waitcnt vmcnt(4)
	v_mov_b32_e32 v42, v228
	v_mov_b32_e32 v43, v229
	v_mov_b32_e32 v44, v230
	v_mov_b32_e32 v45, v231
	v_mov_b32_e32 v138, v232
	v_mov_b32_e32 v139, v233
	v_mov_b32_e32 v140, v234
	v_mov_b32_e32 v141, v235
	v_mov_b32_e32 v162, v236
	v_mov_b32_e32 v163, v237
	v_mov_b32_e32 v164, v238
	v_mov_b32_e32 v165, v239
	v_mov_b32_e32 v166, v240
	v_mov_b32_e32 v167, v241
	v_mov_b32_e32 v168, v242
	v_mov_b32_e32 v169, v243
	s_mov_b64 s[0:1], 0xb0000
	v_add_co_u32_e32 v170, vcc, s2, v160
	s_nop 0
	v_pk_fma_f32 v[68:69], v[24:25], v[144:145], v[44:45]
	v_addc_co_u32_e32 v171, vcc, 0, v161, vcc
	v_pk_fma_f32 v[66:67], v[22:23], v[146:147], v[42:43]
	s_nop 0
	v_pk_fma_f32 v[44:45], v[12:13], v[148:149], v[140:141]
	v_pk_fma_f32 v[42:43], v[10:11], v[150:151], v[138:139]
	s_nop 0
	v_pk_fma_f32 v[24:25], v[128:129], v[152:153], v[164:165]
	v_pk_fma_f32 v[22:23], v[126:127], v[154:155], v[162:163]
	s_nop 0
	v_pk_fma_f32 v[12:13], v[124:125], v[156:157], v[168:169]
	v_pk_fma_f32 v[10:11], v[122:123], v[158:159], v[166:167]
	v_lshl_add_u64 v[126:127], v[160:161], 0, s[0:1]
	s_waitcnt vmcnt(0)
	v_mov_b32_e32 v122, v196
	v_mov_b32_e32 v123, v197
	v_mov_b32_e32 v124, v198
	v_mov_b32_e32 v125, v199
	v_mov_b32_e32 v160, v200
	v_mov_b32_e32 v161, v201
	v_mov_b32_e32 v162, v202
	v_mov_b32_e32 v163, v203
	v_mov_b32_e32 v164, v204
	v_mov_b32_e32 v165, v205
	v_mov_b32_e32 v166, v206
	v_mov_b32_e32 v167, v207
	v_mov_b32_e32 v168, v208
	v_mov_b32_e32 v169, v209
	v_mov_b32_e32 v170, v210
	v_mov_b32_e32 v171, v211
	s_nop 0
	v_mbcnt_lo_u32_b32 v126, -1, 0
	v_mbcnt_hi_u32_b32 v126, -1, v126
	v_and_b32_e32 v128, 64, v126
	v_xor_b32_e32 v127, 16, v126
	v_add_u32_e32 v128, 64, v128
	v_cmp_lt_i32_e64 s[0:1], v127, v128
	v_mul_f32_e32 v139, v113, v113
	v_mul_f32_e32 v140, v95, v95
	v_cndmask_b32_e64 v127, v126, v127, s[0:1]
	v_lshlrev_b32_e32 v138, 2, v127
	v_mul_f32_e32 v127, v111, v111
	v_mul_f32_e32 v141, v97, v97
	v_fmac_f32_e32 v127, v110, v110
	v_fmac_f32_e32 v139, v112, v112
	v_fmac_f32_e32 v140, v94, v94
	v_fmac_f32_e32 v141, v96, v96
	v_add_f32_e32 v127, v127, v139
	v_add_f32_e32 v139, v140, v141
	v_add_f32_e32 v140, v172, v173
	v_add_f32_e32 v127, v127, v139
	v_add_f32_e32 v141, v174, v175
	v_add_f32_e32 v127, v140, v127
	v_add_f32_e32 v127, v141, v127
	ds_bpermute_b32 v140, v138, v127
	v_xor_b32_e32 v129, 32, v126
	v_cmp_lt_i32_e64 s[0:1], v129, v128
	v_cmp_gt_u32_e32 vcc, 16, v1
	s_waitcnt lgkmcnt(0)
	v_add_f32_e32 v140, v127, v140
	v_cndmask_b32_e64 v126, v126, v129, s[0:1]
	v_lshlrev_b32_e32 v139, 2, v126
	ds_bpermute_b32 v141, v139, v140
	s_lshl_b32 s0, s17, 2
	s_add_i32 s2, s0, 0
	s_nop 0
	v_pk_fma_f32 v[128:129], v[120:121], v[144:145], v[124:125]
	v_pk_fma_f32 v[126:127], v[118:119], v[146:147], v[122:123]
	s_nop 0
	v_pk_fma_f32 v[124:125], v[116:117], v[148:149], v[162:163]
	v_pk_fma_f32 v[122:123], v[114:115], v[150:151], v[160:161]
	s_nop 0
	v_pk_fma_f32 v[120:121], v[136:137], v[152:153], v[166:167]
	v_pk_fma_f32 v[118:119], v[134:135], v[154:155], v[164:165]
	s_nop 0
	v_pk_fma_f32 v[116:117], v[132:133], v[156:157], v[170:171]
	v_pk_fma_f32 v[114:115], v[130:131], v[158:159], v[168:169]
	s_nop 0
	s_and_saveexec_b64 s[0:1], vcc
	v_readlane_b32 s96, v254, 22
	v_readlane_b32 s97, v254, 23
	s_mov_b32 s62, s27
	s_cbranch_execz .LBB0_245
	s_lshl_b32 s3, s21, 10
	s_add_i32 s3, s2, s3
	v_lshl_add_u32 v130, v190, 4, s3
	s_waitcnt lgkmcnt(0)
	v_add_f32_e32 v131, v140, v141
	ds_write_b32 v130, v131
